# v26 plus swa cache-out pass as a straight-line fast path for the 256-block grid (8 loads in flight, one wait) with the original loop kept for other grids
# speedup vs baseline: 1.0219x; 1.0049x over previous
; DI float bf_lo(unsigned w) { return __uint_as_float(w << 16); }
; DI void pass_swa_cache_out(const Params& p, int tid) {
;     const bf16_t* P = (const bf16_t*)(p.ws + WS_P);
;     const int gt = blockIdx.x * 512 + tid, GT = gridDim.x * 512;
;     for (int i = gt; i < 4 * 262144; i += GT) { const int which = i >> 18, r = i & 262143, b = r >> 14, j = (r >> 7) & 127, c = r & 127;
;         const bool isv = which >= 2, samp = which & 1; float v;
;         if (!samp) v = bf_lo((unsigned)P[G_SKV + (size_t)(b * SEQ + SEQ - 128 + j) * 256 + (isv ? 128 : 0) + c]);
;     ...
;         else v = bf_lo((unsigned)P[G_SKV + (size_t)(MP + b * 64 + j - 64) * 256 + (isv ? 128 : 0) + c]);
;         p.out[(which == 0 ? O_KP : which == 1 ? O_KS : which == 2 ? O_VP : O_VS) + r] = v; }
; }
.LBB0_519:
	s_or_b64 exec, exec, s[0:1]
	s_cmpk_lg_i32 s65, 0x100
	s_cbranch_scc1 .Lco_generic
	v_lshl_add_u32 v1, s64, 9, v153
	v_and_b32_e32 v0, 0x7f, v1
	v_bfe_u32 v2, v1, 7, 7
	v_lshrrev_b32_e32 v3, 14, v1
	v_lshlrev_b32_e32 v4, 21, v3
	v_lshl_or_b32 v4, v2, 9, v4
	v_lshl_add_u32 v4, v0, 1, v4
	v_add_u32_e32 v5, 0x1000000, v4
	s_add_u32 s4, s82, 0x28bf0000
	s_addc_u32 s5, s83, 0
	global_load_ushort v20, v4, s[4:5]
	global_load_ushort v21, v5, s[4:5]
	global_load_ushort v24, v4, s[4:5] offset:256
	global_load_ushort v25, v5, s[4:5] offset:256
	v_cmp_gt_u32_e32 vcc, 64, v2
	s_cbranch_vccz .Lco_samp_hi
	v_lshlrev_b32_e32 v10, 14, v3
	v_lshl_or_b32 v10, v2, 7, v10
	v_or_b32_e32 v10, v10, v0
	v_lshlrev_b32_e32 v10, 2, v10
	v_add_u32_e32 v10, 0x8000, v10
	v_add_u32_e32 v11, 0x80000, v10
	global_load_dword v22, v10, s[78:79]
	global_load_dword v23, v11, s[78:79]
	global_load_dword v26, v10, s[80:81]
	global_load_dword v27, v11, s[80:81]
	s_waitcnt vmcnt(0)
	s_branch .Lco_cvt
.Lco_samp_hi:
	v_lshlrev_b32_e32 v10, 14, v3
	v_lshl_add_u32 v10, v2, 8, v10
	v_lshlrev_b32_e32 v10, 1, v10
	v_or_b32_e32 v10, 0x2000000, v10
	v_lshl_add_u32 v10, v0, 1, v10
	v_add_u32_e32 v11, 0x40000, v10
	s_add_u32 s6, s82, 0x289f8000
	s_addc_u32 s7, s83, 0
	global_load_ushort v22, v10, s[6:7]
	global_load_ushort v23, v11, s[6:7]
	global_load_ushort v26, v10, s[6:7] offset:256
	global_load_ushort v27, v11, s[6:7] offset:256
	s_waitcnt vmcnt(0)
	v_lshlrev_b32_e32 v22, 16, v22
	v_lshlrev_b32_e32 v23, 16, v23
	v_lshlrev_b32_e32 v26, 16, v26
	v_lshlrev_b32_e32 v27, 16, v27
.Lco_cvt:
	v_lshlrev_b32_e32 v20, 16, v20
	v_lshlrev_b32_e32 v21, 16, v21
	v_lshlrev_b32_e32 v24, 16, v24
	v_lshlrev_b32_e32 v25, 16, v25
	v_lshlrev_b32_e32 v8, 2, v1
	v_add_u32_e32 v9, 0x80000, v8
	s_add_u32 s4, s92, 0x12400000
	s_addc_u32 s5, s93, 0
	global_store_dword v8, v20, s[4:5]
	global_store_dword v9, v21, s[4:5]
	s_add_u32 s4, s92, 0x12500000
	s_addc_u32 s5, s93, 0
	global_store_dword v8, v22, s[4:5]
	global_store_dword v9, v23, s[4:5]
	s_add_u32 s4, s92, 0x12600000
	s_addc_u32 s5, s93, 0
	global_store_dword v8, v24, s[4:5]
	global_store_dword v9, v25, s[4:5]
	s_add_u32 s4, s92, 0x12700000
	s_addc_u32 s5, s93, 0
	global_store_dword v8, v26, s[4:5]
	global_store_dword v9, v27, s[4:5]
	s_branch .LBB0_530
.Lco_generic:
	v_lshl_add_u32 v1, s64, 9, v153
	s_mov_b32 s0, 0x100000
	v_cmp_gt_i32_e32 vcc, s0, v1
	s_and_saveexec_b64 s[2:3], vcc
	s_cbranch_execz .LBB0_530
	v_and_b32_e32 v0, 0x7f, v153
	s_lshl_b32 s10, s65, 9
	v_mov_b32_e32 v3, 0
	s_mov_b64 s[4:5], 0
	s_mov_b32 s11, 0x3ffff
	v_mov_b32_e32 v7, 0x49c0000
	v_mov_b32_e32 v8, 0x4980000
	v_mov_b32_e32 v9, 0x4940000
	v_mov_b32_e32 v10, 0x4900000
	s_mov_b32 s12, 0xfffff
	v_mov_b32_e32 v11, 0x100
	v_bfrev_b32_e32 v12, 64
	v_lshlrev_b32_e32 v4, 1, v0
	s_branch .LBB0_522
